# GEMM prologues: all fourteen leading LDS-DMA loads issued before the first wait and barrier (prologue de-serialisation)
# baseline (speedup 1.0000x reference)
.LBB0_169:
	s_lshl_b32 s5, s5, 5
	s_mov_b64 s[10:11], 0x80
	s_and_b32 s5, s5, 0x60
	s_add_i32 m0, s30, 0x18000
	v_lshl_add_u64 v[6:7], v[6:7], 0, s[10:11]
	s_lshl_b32 s7, s4, 13
	s_lshl_b32 s9, s5, 7
	global_load_lds_dwordx4 v[6:7], off
	v_lshl_add_u64 v[4:5], v[4:5], 0, s[10:11]
	s_add_i32 m0, s30, 0x1a000
	s_add_i32 s38, s30, 0x8000
	s_add_i32 s39, s30, 0xa000
	global_load_lds_dwordx4 v[4:5], off
	v_lshl_add_u64 v[2:3], v[2:3], 0, s[10:11]
	s_mov_b32 m0, s38
	s_add_u32 s12, s26, 0x40080
	global_load_lds_dwordx4 v[2:3], off
	v_lshl_add_u64 v[0:1], v[0:1], 0, s[10:11]
	s_mov_b32 m0, s39
	s_addc_u32 s13, s27, 0
	global_load_lds_dwordx4 v[0:1], off
	s_add_i32 m0, s30, 0x1c000
	v_lshl_add_u64 v[0:1], s[12:13], 0, v[130:131]
	global_load_lds_dwordx4 v[0:1], off
	v_lshl_add_u64 v[0:1], s[12:13], 0, v[134:135]
	s_add_i32 m0, s30, 0x1e000
	v_readlane_b32 s16, v252, 0
	global_load_lds_dwordx4 v[0:1], off
	s_waitcnt vmcnt(8)
	s_barrier
	v_lshrrev_b32_e32 v1, 1, v8
	v_and_b32_e32 v1, 24, v1
	v_and_b32_e32 v0, 15, v8
	v_lshlrev_b32_e32 v2, 1, v1
	v_lshl_or_b32 v160, s4, 6, v0
	v_lshl_or_b32 v0, v0, 6, v2
	v_lshlrev_b32_e32 v2, 2, v8
	v_and_b32_e32 v2, 32, v2
	v_bitop3_b32 v3, v0, s7, v2 bitop3:0xde
	v_bitop3_b32 v161, v0, s9, v2 bitop3:0xde
	v_lshlrev_b32_e32 v0, 14, v9
	v_and_b32_e32 v0, 0xffff8000, v0
	v_or_b32_e32 v162, s5, v1
	v_lshl_add_u32 v0, v10, 11, v0
	v_and_b32_e32 v1, 1, v9
	s_cmpk_lt_u32 s2, 0x100
	v_readlane_b32 s22, v252, 6
	v_lshl_or_b32 v0, v1, 6, v0
	s_cselect_b64 s[12:13], -1, 0
	v_readlane_b32 s23, v252, 7
	s_add_u32 s14, s22, 0x2120000
	v_lshl_add_u32 v142, v11, 1, v0
	v_lshlrev_b32_e32 v0, 14, v12
	s_addc_u32 s15, s23, 0
	v_and_b32_e32 v0, 0xffff8000, v0
	s_waitcnt vmcnt(6)
	s_add_u32 s40, s22, 0x5180000
	v_lshl_add_u32 v0, v13, 11, v0
	v_and_b32_e32 v1, 1, v12
	s_addc_u32 s41, s23, 0
	v_lshlrev_b32_e32 v136, 1, v162
	v_lshl_or_b32 v0, v1, 6, v0
	s_add_i32 s45, 0, 0x10000
	s_add_i32 s46, 0, 0x14000
	v_lshrrev_b32_e32 v138, 1, v162
	v_readlane_b32 s18, v252, 2
	v_lshl_add_u64 v[140:141], s[22:23], 0, v[136:137]
	s_ashr_i32 s42, s86, 31
	s_mov_b32 s43, s86
	s_ashr_i32 s44, s54, 31
	v_mov_b32_e32 v143, v137
	v_lshl_add_u32 v144, v14, 1, v0
	v_mov_b32_e32 v145, v137
	v_mov_b64_e32 v[146:147], 0x600
	v_mov_b64_e32 v[148:149], 0x5ff
	v_add_u32_e32 v163, s45, v161
	v_add_u32_e32 v164, s46, v161
	v_add_u32_e32 v165, 0, v3
	s_movk_i32 s47, 0x3ff
	s_movk_i32 s48, 0xfa00
	s_mov_b32 s49, 0x1020000
	v_mov_b32_e32 v166, 0x46800000
	v_mov_b32_e32 v167, 0x3db504f3
	s_barrier
	v_readlane_b32 s17, v252, 1
	v_readlane_b32 s19, v252, 3
	v_readlane_b32 s20, v252, 4
	v_readlane_b32 s21, v252, 5
	s_branch .LBB0_172

.LBB0_669:
	s_lshl_b32 s8, s8, 5
	s_and_b32 s14, s8, 0x60
	s_mov_b64 s[8:9], 0x80
	s_add_i32 m0, s33, 0x18000
	v_lshl_add_u64 v[6:7], v[6:7], 0, s[8:9]
	s_lshl_b32 s11, s5, 13
	s_lshl_b32 s15, s14, 7
	global_load_lds_dwordx4 v[6:7], off
	v_lshl_add_u64 v[4:5], v[4:5], 0, s[8:9]
	s_add_i32 m0, s33, 0x1a000
	s_add_i32 s47, s33, 0x8000
	s_add_i32 s48, s33, 0xa000
	global_load_lds_dwordx4 v[4:5], off
	v_lshl_add_u64 v[0:1], v[0:1], 0, s[8:9]
	s_mov_b32 m0, s47
	s_add_u32 s12, s40, 0x20080
	global_load_lds_dwordx4 v[0:1], off
	v_lshl_add_u64 v[0:1], v[2:3], 0, s[8:9]
	s_mov_b32 m0, s48
	s_addc_u32 s13, s41, 0
	global_load_lds_dwordx4 v[0:1], off
	s_add_i32 m0, s33, 0x1c000
	v_lshl_add_u64 v[0:1], s[12:13], 0, v[130:131]
	global_load_lds_dwordx4 v[0:1], off
	v_lshl_add_u64 v[0:1], s[12:13], 0, v[134:135]
	s_add_i32 m0, s33, 0x1e000
	v_readlane_b32 s56, v252, 0
	global_load_lds_dwordx4 v[0:1], off
	s_waitcnt vmcnt(8)
	s_barrier
	v_lshrrev_b32_e32 v1, 1, v8
	v_and_b32_e32 v1, 24, v1
	v_and_b32_e32 v0, 15, v8
	v_lshlrev_b32_e32 v2, 1, v1
	v_lshl_or_b32 v148, s5, 6, v0
	v_lshl_or_b32 v0, v0, 6, v2
	v_lshlrev_b32_e32 v2, 2, v8
	v_and_b32_e32 v2, 32, v2
	v_bitop3_b32 v3, v0, s11, v2 bitop3:0xde
	v_bitop3_b32 v149, v0, s15, v2 bitop3:0xde
	v_lshlrev_b32_e32 v0, 13, v9
	v_and_b32_e32 v0, 0xffffc000, v0
	v_or_b32_e32 v150, s14, v1
	v_lshl_add_u32 v0, v10, 10, v0
	v_and_b32_e32 v1, 1, v9
	v_readlane_b32 s57, v252, 1
	v_readlane_b32 s58, v252, 2
	v_readlane_b32 s59, v252, 3
	v_readlane_b32 s60, v252, 4
	v_readlane_b32 s61, v252, 5
	v_lshl_or_b32 v0, v1, 6, v0
	v_readlane_b32 s62, v252, 6
	v_readlane_b32 s63, v252, 7
	s_mov_b64 s[56:57], s[60:61]
	v_lshl_add_u32 v136, v11, 1, v0
	v_lshlrev_b32_e32 v0, 13, v12
	s_cmpk_lt_u32 s10, 0x100
	s_mov_b64 s[58:59], s[62:63]
	v_and_b32_e32 v0, 0xffffc000, v0
	s_waitcnt vmcnt(6)
	s_cselect_b64 s[10:11], -1, 0
	s_add_u32 s12, s58, 0x9200000
	v_lshl_add_u32 v0, v13, 10, v0
	v_and_b32_e32 v1, 1, v12
	s_addc_u32 s13, s59, 0
	v_lshl_or_b32 v0, v1, 6, v0
	s_add_i32 s51, 0, 0x10000
	s_add_i32 s52, 0, 0x14000
	s_sext_i32_i8 s53, s4
	s_ashr_i32 s49, s86, 31
	s_mov_b32 s50, s86
	v_mov_b32_e32 v137, v131
	v_lshl_add_u32 v138, v14, 1, v0
	v_mov_b32_e32 v139, v131
	v_mov_b64_e32 v[140:141], 0x100
	v_mov_b64_e32 v[142:143], 0xff
	v_add_u32_e32 v151, s51, v149
	v_add_u32_e32 v152, s52, v149
	v_add_u32_e32 v153, 0, v3
	s_barrier
	s_branch .LBB0_672

.LBB0_698:
	s_mov_b64 s[12:13], 0x80
	s_add_i32 m0, s35, 0x18000
	v_lshl_add_u64 v[6:7], v[6:7], 0, s[12:13]
	global_load_lds_dwordx4 v[6:7], off
	v_lshl_add_u64 v[4:5], v[4:5], 0, s[12:13]
	s_add_i32 m0, s35, 0x1a000
	s_add_i32 s46, s35, 0x8000
	s_add_i32 s47, s35, 0xa000
	global_load_lds_dwordx4 v[4:5], off
	v_lshl_add_u64 v[0:1], v[0:1], 0, s[12:13]
	s_mov_b32 m0, s46
	s_add_u32 s0, s38, 0x40080
	global_load_lds_dwordx4 v[0:1], off
	v_lshl_add_u64 v[0:1], v[2:3], 0, s[12:13]
	s_mov_b32 m0, s47
	s_addc_u32 s1, s39, 0
	global_load_lds_dwordx4 v[0:1], off
	s_add_i32 m0, s35, 0x1c000
	v_lshl_add_u64 v[0:1], s[0:1], 0, v[132:133]
	global_load_lds_dwordx4 v[0:1], off
	v_lshl_add_u64 v[0:1], s[0:1], 0, v[136:137]
	s_add_i32 m0, s35, 0x1e000
	s_movk_i32 s0, 0x100
	global_load_lds_dwordx4 v[0:1], off
	s_waitcnt vmcnt(8)
	s_barrier
	s_waitcnt vmcnt(6)
	v_cmp_gt_i32_e32 vcc, s0, v8
	s_barrier
	s_and_saveexec_b64 s[16:17], vcc
	s_cbranch_execz .LBB0_700
	v_lshl_add_u32 v0, s34, 8, v8
	v_ashrrev_i32_e32 v1, 31, v0
	v_readlane_b32 s48, v252, 0
	v_lshlrev_b64 v[0:1], 6, v[0:1]
	v_readlane_b32 s54, v252, 6
	v_readlane_b32 s55, v252, 7
	s_mov_b64 s[0:1], 0xe2a0000
	v_mov_b32_e32 v26, 0x358637bd
	v_lshl_add_u64 v[16:17], s[54:55], 0, v[0:1]
	v_lshl_add_u64 v[20:21], v[16:17], 0, s[0:1]
	v_add_co_u32_e32 v16, vcc, 0xe2a0000, v16
	global_load_dwordx4 v[0:3], v[20:21], off offset:32
	global_load_dwordx4 v[4:7], v[20:21], off offset:16
	v_addc_co_u32_e32 v17, vcc, 0, v17, vcc
	global_load_dwordx4 v[16:19], v[16:17], off
	s_mov_b32 s27, 0xf800000
	global_load_dwordx4 v[20:23], v[20:21], off offset:48
	v_mov_b32_e32 v27, 0x260
	v_readlane_b32 s49, v252, 1
	v_readlane_b32 s50, v252, 2
	v_readlane_b32 s51, v252, 3
	v_readlane_b32 s52, v252, 4
	v_readlane_b32 s53, v252, 5
	s_waitcnt vmcnt(0)
	v_mov_b32_e32 v24, v5
	v_mov_b32_e32 v25, v6
	v_mov_b32_e32 v5, v7
	v_mov_b32_e32 v6, v1
	v_mov_b32_e32 v7, v2
	v_mov_b32_e32 v1, v3
	v_mov_b32_e32 v2, v17
	v_mov_b32_e32 v3, v18
	v_mov_b32_e32 v17, v19
	v_pk_add_f32 v[4:5], v[24:25], v[4:5]
	v_pk_add_f32 v[0:1], v[6:7], v[0:1]
	v_pk_add_f32 v[2:3], v[2:3], v[16:17]
	v_add_f32_e32 v4, v4, v5
	v_add_f32_e32 v0, v0, v1
	v_add_f32_e32 v1, v2, v3
	v_fmamk_f32 v2, v4, 0x3b800000, v26
	v_fmamk_f32 v0, v0, 0x3b800000, v26
	v_mul_f32_e32 v3, 0x4f800000, v2
	v_cmp_gt_f32_e32 vcc, s27, v2
	v_fmamk_f32 v1, v1, 0x3b800000, v26
	v_mul_f32_e32 v4, 0x4f800000, v0
	v_cndmask_b32_e32 v2, v2, v3, vcc
	v_cmp_gt_f32_e64 s[0:1], s27, v0
	v_mul_f32_e32 v5, 0x4f800000, v1
	v_sqrt_f32_e32 v3, v2
	v_cndmask_b32_e64 v0, v0, v4, s[0:1]
	v_cmp_gt_f32_e64 s[6:7], s27, v1
	v_sqrt_f32_e32 v4, v0
	v_add_u32_e32 v6, -1, v3
	v_cndmask_b32_e64 v1, v1, v5, s[6:7]
	v_sqrt_f32_e32 v5, v1
	v_add_u32_e32 v16, -1, v4
	v_fma_f32 v24, -v6, v3, v2
	v_add_u32_e32 v7, 1, v3
	v_add_u32_e32 v18, -1, v5
	v_fma_f32 v28, -v16, v4, v0
	v_cmp_ge_f32_e64 s[8:9], 0, v24
	v_add_u32_e32 v17, 1, v4
	v_fma_f32 v25, -v7, v3, v2
	v_fma_f32 v30, -v18, v5, v1
	v_cndmask_b32_e64 v3, v3, v6, s[8:9]
	v_cmp_ge_f32_e64 s[8:9], 0, v28
	v_add_u32_e32 v19, 1, v5
	v_fma_f32 v29, -v17, v4, v0
	v_cndmask_b32_e64 v4, v4, v16, s[8:9]
	v_cmp_ge_f32_e64 s[8:9], 0, v30
	v_fma_f32 v31, -v19, v5, v1
	s_nop 0
	v_cndmask_b32_e64 v5, v5, v18, s[8:9]
	v_cmp_lt_f32_e64 s[8:9], 0, v25
	s_nop 1
	v_cndmask_b32_e64 v3, v3, v7, s[8:9]
	v_cmp_lt_f32_e64 s[8:9], 0, v29
	v_mul_f32_e32 v6, 0x37800000, v3
	v_cndmask_b32_e32 v3, v3, v6, vcc
	v_cndmask_b32_e64 v4, v4, v17, s[8:9]
	v_cmp_lt_f32_e64 s[8:9], 0, v31
	v_mul_f32_e32 v7, 0x37800000, v4
	v_cmp_class_f32_e32 vcc, v2, v27
	v_cndmask_b32_e64 v5, v5, v19, s[8:9]
	v_mul_f32_e32 v16, 0x37800000, v5
	v_cndmask_b32_e64 v4, v4, v7, s[0:1]
	v_cndmask_b32_e32 v2, v3, v2, vcc
	v_cmp_class_f32_e32 vcc, v0, v27
	v_cndmask_b32_e64 v5, v5, v16, s[6:7]
	s_nop 0
	v_cndmask_b32_e32 v3, v4, v0, vcc
	v_cmp_class_f32_e32 vcc, v1, v27
	s_nop 1
	v_cndmask_b32_e32 v0, v5, v1, vcc
	v_div_scale_f32 v1, s[0:1], v2, v2, 1.0
	v_div_scale_f32 v6, s[6:7], v0, v0, 1.0
	v_rcp_f32_e32 v7, v1
	v_rcp_f32_e32 v17, v6
	v_div_scale_f32 v4, s[0:1], 1.0, v2, 1.0
	v_fma_f32 v19, -v1, v7, 1.0
	v_fma_f32 v25, -v6, v17, 1.0
	v_div_scale_f32 v18, vcc, 1.0, v0, 1.0
	v_fmac_f32_e32 v7, v19, v7
	v_fmac_f32_e32 v17, v25, v17
	v_mul_f32_e32 v19, v4, v7
	v_mul_f32_e32 v25, v18, v17
	v_fma_f32 v28, -v1, v19, v4
	v_fma_f32 v29, -v6, v25, v18
	v_fmac_f32_e32 v19, v28, v7
	v_fmac_f32_e32 v25, v29, v17
	v_fma_f32 v1, -v1, v19, v4
	v_fma_f32 v4, -v6, v25, v18
	v_div_fmas_f32 v4, v4, v17, v25
	s_mov_b64 vcc, s[0:1]
	v_div_fixup_f32 v4, v4, v0, 1.0
	v_div_fmas_f32 v0, v1, v7, v19
	v_div_scale_f32 v5, s[6:7], v3, v3, 1.0
	v_div_fixup_f32 v2, v0, v2, 1.0
	v_mov_b32_e32 v0, v21
	v_mov_b32_e32 v1, v22
	v_mov_b32_e32 v21, v23
	v_rcp_f32_e32 v16, v5
	v_pk_add_f32 v[0:1], v[0:1], v[20:21]
	v_div_scale_f32 v6, vcc, 1.0, v3, 1.0
	v_add_f32_e32 v0, v0, v1
	v_fmac_f32_e32 v26, 0x3b800000, v0
	v_mul_f32_e32 v0, 0x4f800000, v26
	v_cmp_gt_f32_e64 s[0:1], s27, v26
	v_fma_f32 v24, -v5, v16, 1.0
	v_fmac_f32_e32 v16, v24, v16
	v_cndmask_b32_e64 v0, v26, v0, s[0:1]
	v_sqrt_f32_e32 v1, v0
	v_mul_f32_e32 v7, v6, v16
	v_fma_f32 v17, -v5, v7, v6
	v_fmac_f32_e32 v7, v17, v16
	v_fma_f32 v5, -v5, v7, v6
	v_add_u32_e32 v6, -1, v1
	v_fma_f32 v17, -v6, v1, v0
	v_cmp_ge_f32_e64 s[6:7], 0, v17
	v_add_u32_e32 v17, 1, v1
	v_div_fmas_f32 v5, v5, v16, v7
	v_cndmask_b32_e64 v6, v1, v6, s[6:7]
	v_fma_f32 v1, -v17, v1, v0
	v_cmp_lt_f32_e64 s[6:7], 0, v1
	v_div_fixup_f32 v5, v5, v3, 1.0
	s_nop 0
	v_cndmask_b32_e64 v1, v6, v17, s[6:7]
	v_mul_f32_e32 v6, 0x37800000, v1
	v_cndmask_b32_e64 v1, v1, v6, s[0:1]
	v_cmp_class_f32_e64 s[0:1], v0, v27
	s_nop 1
	v_cndmask_b32_e64 v0, v1, v0, s[0:1]
	v_div_scale_f32 v1, s[0:1], v0, v0, 1.0
	v_rcp_f32_e32 v6, v1
	s_nop 0
	v_fma_f32 v3, -v1, v6, 1.0
	v_fmac_f32_e32 v6, v3, v6
	v_div_scale_f32 v3, vcc, 1.0, v0, 1.0
	v_mul_f32_e32 v7, v3, v6
	v_fma_f32 v16, -v1, v7, v3
	v_fmac_f32_e32 v7, v16, v6
	v_div_scale_f32 v16, s[0:1], v2, v2, v4
	v_rcp_f32_e32 v17, v16
	v_fma_f32 v1, -v1, v7, v3
	v_div_fmas_f32 v1, v1, v6, v7
	v_div_fixup_f32 v3, v1, v0, 1.0
	v_fma_f32 v0, -v16, v17, 1.0
	v_fmac_f32_e32 v17, v0, v17
	v_div_scale_f32 v0, vcc, v4, v2, v4
	v_mul_f32_e32 v1, v0, v17
	v_fma_f32 v6, -v16, v1, v0
	v_fmac_f32_e32 v1, v6, v17
	v_div_scale_f32 v6, s[0:1], v5, v5, v2
	v_rcp_f32_e32 v7, v6
	v_fma_f32 v0, -v16, v1, v0
	v_div_fmas_f32 v0, v0, v17, v1
	v_div_fixup_f32 v0, v0, v2, v4
	v_fma_f32 v1, -v6, v7, 1.0
	v_fmac_f32_e32 v7, v1, v7
	v_div_scale_f32 v1, vcc, v2, v5, v2
	v_mul_f32_e32 v4, v1, v7
	v_fma_f32 v16, -v6, v4, v1
	v_fmac_f32_e32 v4, v16, v7
	v_fma_f32 v1, -v6, v4, v1
	v_div_scale_f32 v6, s[0:1], v3, v3, v5
	v_rcp_f32_e32 v16, v6
	v_div_fmas_f32 v1, v1, v7, v4
	v_div_fixup_f32 v1, v1, v5, v2
	v_fma_f32 v2, -v6, v16, 1.0
	v_fmac_f32_e32 v16, v2, v16
	v_div_scale_f32 v2, vcc, v5, v3, v5
	v_mul_f32_e32 v4, v2, v16
	v_fma_f32 v7, -v6, v4, v2
	v_fmac_f32_e32 v4, v7, v16
	v_fma_f32 v2, -v6, v4, v2
	v_div_fmas_f32 v2, v2, v16, v4
	v_add_u32_e32 v4, 0, v15
	v_div_fixup_f32 v2, v2, v3, v5
	v_add_u32_e32 v4, 0x20000, v4
	ds_write_b128 v4, v[0:3]

.LBB0_783:
	s_mov_b64 s[14:15], 0x80
	s_and_b32 s33, s7, 3
	s_add_i32 m0, s1, 0x18000
	v_lshl_add_u64 v[6:7], v[6:7], 0, s[14:15]
	s_lshl_b32 s7, s2, 13
	s_lshl_b32 s16, s33, 12
	global_load_lds_dwordx4 v[6:7], off
	v_lshl_add_u64 v[4:5], v[4:5], 0, s[14:15]
	s_add_i32 m0, s1, 0x1a000
	s_add_i32 s44, s1, 0x8000
	s_add_i32 s45, s1, 0xa000
	global_load_lds_dwordx4 v[4:5], off
	v_lshl_add_u64 v[2:3], v[2:3], 0, s[14:15]
	s_mov_b32 m0, s44
	s_add_u32 s8, s30, 0x40080
	global_load_lds_dwordx4 v[2:3], off
	v_lshl_add_u64 v[0:1], v[0:1], 0, s[14:15]
	s_mov_b32 m0, s45
	s_addc_u32 s9, s31, 0
	global_load_lds_dwordx4 v[0:1], off
	s_add_i32 m0, s1, 0x1c000
	v_lshl_add_u64 v[0:1], s[8:9], 0, v[130:131]
	global_load_lds_dwordx4 v[0:1], off
	v_lshl_add_u64 v[0:1], s[8:9], 0, v[134:135]
	s_add_i32 m0, s1, 0x1e000
	v_bfe_u32 v148, v178, 4, 2
	global_load_lds_dwordx4 v[0:1], off
	s_waitcnt vmcnt(8)
	s_barrier
	v_and_b32_e32 v179, 15, v178
	v_lshlrev_b32_e32 v0, 4, v148
	v_lshlrev_b32_e32 v1, 2, v178
	v_lshl_or_b32 v0, v179, 6, v0
	v_and_b32_e32 v1, 32, v1
	v_bitop3_b32 v4, v0, s7, v1 bitop3:0xde
	v_bitop3_b32 v151, v0, s16, v1 bitop3:0xde
	v_lshlrev_b32_e32 v0, 14, v8
	v_and_b32_e32 v0, 0xffff8000, v0
	v_lshl_add_u32 v0, v9, 11, v0
	v_and_b32_e32 v1, 1, v8
	v_lshl_or_b32 v0, v1, 6, v0
	s_sext_i32_i8 s10, s6
	s_mov_b64 s[6:7], 0x40080
	v_lshl_add_u32 v0, v10, 1, v0
	v_mov_b32_e32 v1, v131
	v_lshl_add_u64 v[136:137], v[0:1], 0, s[6:7]
	v_lshlrev_b32_e32 v0, 14, v11
	v_and_b32_e32 v0, 0xffff8000, v0
	v_lshl_add_u32 v0, v12, 11, v0
	v_and_b32_e32 v1, 1, v11
	v_lshl_or_b32 v0, v1, 6, v0
	s_waitcnt vmcnt(6)
	v_lshl_add_u32 v0, v13, 1, v0
	v_mov_b32_e32 v1, v131
	v_mov_b32_e32 v2, v131
	v_mov_b32_e32 v3, v131
	v_lshl_add_u64 v[138:139], v[0:1], 0, s[6:7]
	v_mov_b32_e32 v0, v131
	v_add_u32_e32 v152, 0, v4
	v_mov_b64_e32 v[6:7], v[2:3]
	v_mov_b64_e32 v[10:11], v[2:3]
	v_mov_b64_e32 v[14:15], v[2:3]
	v_mov_b64_e32 v[18:19], v[2:3]
	v_mov_b64_e32 v[22:23], v[2:3]
	v_mov_b64_e32 v[26:27], v[2:3]
	v_mov_b64_e32 v[30:31], v[2:3]
	v_mov_b64_e32 v[58:59], v[2:3]
	v_mov_b64_e32 v[66:67], v[2:3]
	v_mov_b64_e32 v[74:75], v[2:3]
	v_mov_b64_e32 v[78:79], v[2:3]
	v_mov_b64_e32 v[82:83], v[2:3]
	v_mov_b64_e32 v[86:87], v[2:3]
	v_mov_b64_e32 v[90:91], v[2:3]
	v_mov_b64_e32 v[94:95], v[2:3]
	v_mov_b64_e32 v[34:35], v[2:3]
	v_mov_b64_e32 v[38:39], v[2:3]
	v_mov_b64_e32 v[42:43], v[2:3]
	v_mov_b64_e32 v[46:47], v[2:3]
	v_mov_b64_e32 v[50:51], v[2:3]
	v_mov_b64_e32 v[54:55], v[2:3]
	v_mov_b64_e32 v[62:63], v[2:3]
	v_mov_b64_e32 v[70:71], v[2:3]
	v_mov_b64_e32 v[98:99], v[2:3]
	v_mov_b64_e32 v[102:103], v[2:3]
	v_mov_b64_e32 v[106:107], v[2:3]
	v_mov_b64_e32 v[110:111], v[2:3]
	v_mov_b64_e32 v[114:115], v[2:3]
	v_mov_b64_e32 v[118:119], v[2:3]
	v_mov_b64_e32 v[122:123], v[2:3]
	v_mov_b64_e32 v[126:127], v[2:3]
	v_lshl_or_b32 v150, s2, 6, v179
	s_mov_b32 s46, 0
	v_mov_b64_e32 v[140:141], 0x100
	v_mov_b64_e32 v[142:143], 0xff
	s_add_i32 s47, 0, 0x10000
	s_add_i32 s48, 0, 0x14000
	v_mov_b64_e32 v[4:5], v[0:1]
	v_mov_b64_e32 v[8:9], v[0:1]
	v_mov_b64_e32 v[12:13], v[0:1]
	v_mov_b64_e32 v[16:17], v[0:1]
	v_mov_b64_e32 v[20:21], v[0:1]
	v_mov_b64_e32 v[24:25], v[0:1]
	v_mov_b64_e32 v[28:29], v[0:1]
	v_mov_b64_e32 v[56:57], v[0:1]
	v_mov_b64_e32 v[64:65], v[0:1]
	v_mov_b64_e32 v[72:73], v[0:1]
	v_mov_b64_e32 v[76:77], v[0:1]
	v_mov_b64_e32 v[80:81], v[0:1]
	v_mov_b64_e32 v[84:85], v[0:1]
	v_mov_b64_e32 v[88:89], v[0:1]
	v_mov_b64_e32 v[92:93], v[0:1]
	v_mov_b64_e32 v[32:33], v[0:1]
	v_mov_b64_e32 v[36:37], v[0:1]
	v_mov_b64_e32 v[40:41], v[0:1]
	v_mov_b64_e32 v[44:45], v[0:1]
	v_mov_b64_e32 v[48:49], v[0:1]
	v_mov_b64_e32 v[52:53], v[0:1]
	v_mov_b64_e32 v[60:61], v[0:1]
	v_mov_b64_e32 v[68:69], v[0:1]
	v_mov_b64_e32 v[96:97], v[0:1]
	v_mov_b64_e32 v[100:101], v[0:1]
	v_mov_b64_e32 v[104:105], v[0:1]
	v_mov_b64_e32 v[108:109], v[0:1]
	v_mov_b64_e32 v[112:113], v[0:1]
	v_mov_b64_e32 v[116:117], v[0:1]
	v_mov_b64_e32 v[120:121], v[0:1]
	v_mov_b64_e32 v[124:125], v[0:1]
	s_barrier

.LBB0_1067:
	s_mov_b64 s[12:13], 0x80
	s_add_i32 m0, s29, 0x18000
	v_lshl_add_u64 v[6:7], v[6:7], 0, s[12:13]
	global_load_lds_dwordx4 v[6:7], off
	v_lshl_add_u64 v[4:5], v[4:5], 0, s[12:13]
	s_add_i32 m0, s29, 0x1a000
	s_add_i32 s40, s29, 0x8000
	s_add_i32 s41, s29, 0xa000
	global_load_lds_dwordx4 v[4:5], off
	v_lshl_add_u64 v[0:1], v[0:1], 0, s[12:13]
	s_mov_b32 m0, s40
	s_add_u32 s0, s34, 0x40080
	global_load_lds_dwordx4 v[0:1], off
	v_lshl_add_u64 v[0:1], v[2:3], 0, s[12:13]
	s_mov_b32 m0, s41
	s_addc_u32 s1, s35, 0
	global_load_lds_dwordx4 v[0:1], off
	s_add_i32 m0, s29, 0x1c000
	v_lshl_add_u64 v[0:1], s[0:1], 0, v[130:131]
	global_load_lds_dwordx4 v[0:1], off
	v_lshl_add_u64 v[0:1], s[0:1], 0, v[134:135]
	s_add_i32 m0, s29, 0x1e000
	s_movk_i32 s0, 0x100
	global_load_lds_dwordx4 v[0:1], off
	s_waitcnt vmcnt(8)
	s_barrier
	s_waitcnt vmcnt(6)
	v_cmp_gt_i32_e32 vcc, s0, v9
	s_barrier
	s_and_saveexec_b64 s[14:15], vcc
	s_cbranch_execz .LBB0_1069
	v_lshl_add_u32 v0, s28, 8, v9
	v_readlane_b32 s44, v252, 0
	v_ashrrev_i32_e32 v1, 31, v0
	v_readlane_b32 s50, v252, 6
	v_readlane_b32 s51, v252, 7
	v_mov_b32_e32 v6, 0x358637bd
	s_mov_b32 s0, 0xf800000
	v_lshl_add_u64 v[0:1], v[0:1], 4, s[50:51]
	v_add_co_u32_e32 v0, vcc, 0xe4b8000, v0
	v_readlane_b32 s45, v252, 1
	s_nop 0
	v_addc_co_u32_e32 v1, vcc, 0, v1, vcc
	global_load_dwordx4 v[0:3], v[0:1], off
	v_readlane_b32 s46, v252, 2
	v_readlane_b32 s47, v252, 3
	v_readlane_b32 s48, v252, 4
	v_readlane_b32 s49, v252, 5
	s_waitcnt vmcnt(0)
	v_mov_b32_e32 v4, v1
	v_mov_b32_e32 v5, v2
	v_mov_b32_e32 v1, v3
	v_pk_add_f32 v[0:1], v[4:5], v[0:1]
	v_mov_b32_e32 v2, 0x260
	v_add_f32_e32 v0, v0, v1
	v_fmac_f32_e32 v6, 0x3a800000, v0
	v_mul_f32_e32 v0, 0x4f800000, v6
	v_cmp_gt_f32_e32 vcc, s0, v6
	s_nop 1
	v_cndmask_b32_e32 v0, v6, v0, vcc
	v_sqrt_f32_e32 v1, v0
	s_nop 0
	v_add_u32_e32 v3, -1, v1
	v_add_u32_e32 v4, 1, v1
	v_fma_f32 v5, -v3, v1, v0
	v_fma_f32 v6, -v4, v1, v0
	v_cmp_ge_f32_e64 s[0:1], 0, v5
	s_nop 1
	v_cndmask_b32_e64 v1, v1, v3, s[0:1]
	v_cmp_lt_f32_e64 s[0:1], 0, v6
	s_nop 1
	v_cndmask_b32_e64 v1, v1, v4, s[0:1]
	v_mul_f32_e32 v3, 0x37800000, v1
	v_cndmask_b32_e32 v1, v1, v3, vcc
	v_cmp_class_f32_e32 vcc, v0, v2
	v_lshl_add_u32 v3, v9, 2, 0
	s_nop 0
	v_cndmask_b32_e32 v0, v1, v0, vcc
	v_div_scale_f32 v1, s[0:1], v0, v0, 1.0
	v_rcp_f32_e32 v2, v1
	v_div_scale_f32 v4, vcc, 1.0, v0, 1.0
	v_fma_f32 v5, -v1, v2, 1.0
	v_fmac_f32_e32 v2, v5, v2
	v_mul_f32_e32 v5, v4, v2
	v_fma_f32 v6, -v1, v5, v4
	v_fmac_f32_e32 v5, v6, v2
	v_fma_f32 v1, -v1, v5, v4
	v_div_fmas_f32 v1, v1, v2, v5
	v_div_fixup_f32 v0, v1, v0, 1.0
	v_add_u32_e32 v1, 0x20000, v3
	ds_write_b32 v1, v0

.LBB0_1150:
	s_mov_b64 s[16:17], 0x80
	s_and_b32 s2, s1, 3
	s_add_i32 m0, s13, 0x18000
	v_lshl_add_u64 v[6:7], v[6:7], 0, s[16:17]
	s_lshl_b32 s1, s11, 13
	s_lshl_b32 s20, s2, 12
	global_load_lds_dwordx4 v[6:7], off
	v_lshl_add_u64 v[4:5], v[4:5], 0, s[16:17]
	s_add_i32 m0, s13, 0x1a000
	s_add_i32 s43, s13, 0x8000
	s_add_i32 s44, s13, 0xa000
	global_load_lds_dwordx4 v[4:5], off
	v_lshl_add_u64 v[2:3], v[2:3], 0, s[16:17]
	s_mov_b32 m0, s43
	s_add_u32 s6, s28, 0x100080
	global_load_lds_dwordx4 v[2:3], off
	v_lshl_add_u64 v[0:1], v[0:1], 0, s[16:17]
	s_mov_b32 m0, s44
	s_addc_u32 s7, s29, 0
	global_load_lds_dwordx4 v[0:1], off
	s_add_i32 m0, s13, 0x1c000
	v_lshl_add_u64 v[0:1], s[6:7], 0, v[130:131]
	global_load_lds_dwordx4 v[0:1], off
	v_lshl_add_u64 v[0:1], s[6:7], 0, v[134:135]
	s_add_i32 m0, s13, 0x1e000
	v_bfe_u32 v149, v148, 4, 2
	global_load_lds_dwordx4 v[0:1], off
	s_waitcnt vmcnt(8)
	s_barrier
	v_and_b32_e32 v152, 15, v148
	v_lshlrev_b32_e32 v0, 4, v149
	v_lshlrev_b32_e32 v1, 2, v148
	v_lshl_or_b32 v0, v152, 6, v0
	v_and_b32_e32 v1, 32, v1
	v_bitop3_b32 v4, v0, s1, v1 bitop3:0xde
	v_bitop3_b32 v153, v0, s20, v1 bitop3:0xde
	v_lshlrev_b32_e32 v0, 16, v8
	v_and_b32_e32 v0, 0xfffe0000, v0
	v_lshl_add_u32 v0, v9, 13, v0
	v_and_b32_e32 v1, 1, v8
	v_lshl_or_b32 v0, v1, 6, v0
	s_sext_i32_i8 s10, s0
	s_mov_b64 s[0:1], 0x100080
	v_lshl_add_u32 v0, v10, 1, v0
	v_mov_b32_e32 v1, v131
	v_lshl_add_u64 v[136:137], v[0:1], 0, s[0:1]
	v_lshlrev_b32_e32 v0, 16, v11
	v_and_b32_e32 v0, 0xfffe0000, v0
	v_lshl_add_u32 v0, v12, 13, v0
	v_and_b32_e32 v1, 1, v11
	v_lshl_or_b32 v0, v1, 6, v0
	s_waitcnt vmcnt(6)
	v_lshl_add_u32 v0, v13, 1, v0
	v_mov_b32_e32 v1, v131
	v_mov_b32_e32 v2, v131
	v_mov_b32_e32 v3, v131
	v_lshl_add_u64 v[138:139], v[0:1], 0, s[0:1]
	v_mov_b32_e32 v0, v131
	v_add_u32_e32 v154, 0, v4
	v_mov_b64_e32 v[6:7], v[2:3]
	v_mov_b64_e32 v[10:11], v[2:3]
	v_mov_b64_e32 v[14:15], v[2:3]
	v_mov_b64_e32 v[18:19], v[2:3]
	v_mov_b64_e32 v[22:23], v[2:3]
	v_mov_b64_e32 v[26:27], v[2:3]
	v_mov_b64_e32 v[30:31], v[2:3]
	v_mov_b64_e32 v[50:51], v[2:3]
	v_mov_b64_e32 v[54:55], v[2:3]
	v_mov_b64_e32 v[66:67], v[2:3]
	v_mov_b64_e32 v[70:71], v[2:3]
	v_mov_b64_e32 v[82:83], v[2:3]
	v_mov_b64_e32 v[86:87], v[2:3]
	v_mov_b64_e32 v[90:91], v[2:3]
	v_mov_b64_e32 v[94:95], v[2:3]
	v_mov_b64_e32 v[34:35], v[2:3]
	v_mov_b64_e32 v[38:39], v[2:3]
	v_mov_b64_e32 v[42:43], v[2:3]
	v_mov_b64_e32 v[46:47], v[2:3]
	v_mov_b64_e32 v[58:59], v[2:3]
	v_mov_b64_e32 v[62:63], v[2:3]
	v_mov_b64_e32 v[74:75], v[2:3]
	v_mov_b64_e32 v[78:79], v[2:3]
	v_mov_b64_e32 v[98:99], v[2:3]
	v_mov_b64_e32 v[102:103], v[2:3]
	v_mov_b64_e32 v[106:107], v[2:3]
	v_mov_b64_e32 v[110:111], v[2:3]
	v_mov_b64_e32 v[114:115], v[2:3]
	v_mov_b64_e32 v[118:119], v[2:3]
	v_mov_b64_e32 v[122:123], v[2:3]
	v_mov_b64_e32 v[126:127], v[2:3]
	v_lshl_or_b32 v150, s11, 6, v152
	s_mov_b32 s45, 0
	v_mov_b64_e32 v[140:141], 0x100
	v_mov_b64_e32 v[142:143], 0xff
	s_add_i32 s46, 0, 0x10000
	s_add_i32 s47, 0, 0x14000
	v_mov_b64_e32 v[4:5], v[0:1]
	v_mov_b64_e32 v[8:9], v[0:1]
	v_mov_b64_e32 v[12:13], v[0:1]
	v_mov_b64_e32 v[16:17], v[0:1]
	v_mov_b64_e32 v[20:21], v[0:1]
	v_mov_b64_e32 v[24:25], v[0:1]
	v_mov_b64_e32 v[28:29], v[0:1]
	v_mov_b64_e32 v[48:49], v[0:1]
	v_mov_b64_e32 v[52:53], v[0:1]
	v_mov_b64_e32 v[64:65], v[0:1]
	v_mov_b64_e32 v[68:69], v[0:1]
	v_mov_b64_e32 v[80:81], v[0:1]
	v_mov_b64_e32 v[84:85], v[0:1]
	v_mov_b64_e32 v[88:89], v[0:1]
	v_mov_b64_e32 v[92:93], v[0:1]
	v_mov_b64_e32 v[32:33], v[0:1]
	v_mov_b64_e32 v[36:37], v[0:1]
	v_mov_b64_e32 v[40:41], v[0:1]
	v_mov_b64_e32 v[44:45], v[0:1]
	v_mov_b64_e32 v[56:57], v[0:1]
	v_mov_b64_e32 v[60:61], v[0:1]
	v_mov_b64_e32 v[72:73], v[0:1]
	v_mov_b64_e32 v[76:77], v[0:1]
	v_mov_b64_e32 v[96:97], v[0:1]
	v_mov_b64_e32 v[100:101], v[0:1]
	v_mov_b64_e32 v[104:105], v[0:1]
	v_mov_b64_e32 v[108:109], v[0:1]
	v_mov_b64_e32 v[112:113], v[0:1]
	v_mov_b64_e32 v[116:117], v[0:1]
	v_mov_b64_e32 v[120:121], v[0:1]
	v_mov_b64_e32 v[124:125], v[0:1]
	s_barrier
